# FFN-up K loop: first iteration peeled, its first MFMA into each accumulator takes C=0 (128 accumulator-zeroing v_mov per tile removed)
# speedup vs baseline: 1.0073x; 1.0071x over previous
.LBB0_739:
	s_ashr_i32 s59, s58, 31
	s_lshl_b64 s[18:19], s[58:59], 19
	s_add_u32 s60, s16, s18
	s_addc_u32 s61, s33, s19
	s_and_b64 s[18:19], s[6:7], exec
	s_cselect_b32 s59, s61, s67
	s_cselect_b32 s81, s60, s66
	s_ashr_i32 s31, s30, 31
	s_lshl_b64 s[18:19], s[30:31], 19
	s_add_u32 s62, s5, s18
	s_addc_u32 s63, s46, s19
	s_and_b64 s[18:19], s[6:7], exec
	s_cselect_b32 s31, s63, s39
	s_cselect_b32 s82, s62, s38
	s_add_u32 s83, s38, 0x100
	s_addc_u32 s84, s39, 0
	s_mov_b32 s85, -2
	s_lshl_b32 s18, s64, 8
	s_add_i32 s18, s18, s75
	v_and_or_b32 v252, v217, 15, s18
	v_bfe_u32 v253, v217, 4, 2
	v_lshlrev_b32_e32 v252, 6, v252
	v_lshl_add_u32 v252, v253, 4, v252
	v_mov_b32_e32 v253, 0
	v_mov_b64_e32 v[184:185], 0x2000
	v_lshl_add_u64 v[252:253], s[10:11], 0, v[252:253]
	v_lshl_add_u64 v[184:185], v[252:253], 0, v[184:185]
	s_add_u32 s18, s66, 0x80
	s_addc_u32 s19, s67, 0
	s_add_u32 s66, s66, 0x100
	s_addc_u32 s67, s67, 0
	s_cmp_eq_u32 s85, 12
	s_cselect_b32 s42, s81, s66
	s_cselect_b32 s43, s59, s67
	s_cselect_b32 s45, s31, s84
	s_cselect_b32 s44, s82, s83
	s_add_u32 s38, s42, 0x80
	s_addc_u32 s39, s43, 0
	s_add_u32 s68, s44, 0x80
	s_addc_u32 s69, s45, 0
	s_add_i32 s35, 0, 0x10000
	s_add_i32 s49, 0, 0x14000
	v_add_u32_e32 v96, s35, v151
	v_add_u32_e32 v150, s49, v151
	ds_read_b128 v[138:141], v96
	ds_read_b128 v[142:145], v96 offset:1024
	ds_read_b128 v[146:149], v96 offset:2048
	ds_read_b128 v[156:159], v96 offset:3072
	ds_read_b128 v[160:163], v150
	ds_read_b128 v[164:167], v150 offset:1024
	ds_read_b128 v[168:171], v150 offset:2048
	ds_read_b128 v[172:175], v150 offset:3072
	s_mov_b32 m0, s77
	ds_read_b128 v[176:179], v155
	ds_read_b128 v[180:183], v155 offset:1024
	ds_read_b128 v[190:193], v155 offset:2048
	ds_read_b128 v[194:197], v155 offset:3072
	ds_read_b128 v[198:201], v155 offset:4096
	ds_read_b128 v[202:205], v155 offset:5120
	ds_read_b128 v[206:209], v155 offset:6144
	ds_read_b128 v[210:213], v155 offset:7168
	global_load_lds_dwordx4 v136, s[18:19]
	s_mov_b32 m0, s78
	s_nop 0
	global_load_lds_dwordx4 v132, s[18:19]
	s_add_u32 s18, s18, 0x40000
	s_addc_u32 s19, s19, 0
	s_add_i32 m0, s65, 0xc000
	s_nop 0
	global_load_lds_dwordx4 v136, s[18:19]
	s_add_i32 m0, s65, 0xe000
	s_nop 0
	global_load_lds_dwordx4 v132, s[18:19]
	s_waitcnt vmcnt(8)
	s_waitcnt lgkmcnt(0)
	s_barrier
	s_setprio 1
	s_waitcnt lgkmcnt(0)
	v_mfma_f32_16x16x32_bf16 v[126:129], v[138:141], v[176:179], 0
	v_mfma_f32_16x16x32_bf16 v[118:121], v[146:149], v[176:179], 0
	v_mfma_f32_16x16x32_bf16 v[110:113], v[138:141], v[190:193], 0
	v_mfma_f32_16x16x32_bf16 v[102:105], v[146:149], v[190:193], 0
	v_mfma_f32_16x16x32_bf16 v[92:95], v[138:141], v[198:201], 0
	v_mfma_f32_16x16x32_bf16 v[84:87], v[146:149], v[198:201], 0
	v_mfma_f32_16x16x32_bf16 v[76:79], v[138:141], v[206:209], 0
	v_mfma_f32_16x16x32_bf16 v[68:71], v[146:149], v[206:209], 0
	v_mfma_f32_16x16x32_bf16 v[126:129], v[142:145], v[180:183], v[126:129]
	v_mfma_f32_16x16x32_bf16 v[118:121], v[156:159], v[180:183], v[118:121]
	v_mfma_f32_16x16x32_bf16 v[110:113], v[142:145], v[194:197], v[110:113]
	v_mfma_f32_16x16x32_bf16 v[102:105], v[156:159], v[194:197], v[102:105]
	v_mfma_f32_16x16x32_bf16 v[92:95], v[142:145], v[202:205], v[92:95]
	v_mfma_f32_16x16x32_bf16 v[84:87], v[156:159], v[202:205], v[84:87]
	v_mfma_f32_16x16x32_bf16 v[76:79], v[142:145], v[210:213], v[76:79]
	v_mfma_f32_16x16x32_bf16 v[68:71], v[156:159], v[210:213], v[68:71]
	v_mfma_f32_16x16x32_bf16 v[122:125], v[160:163], v[176:179], 0
	v_mfma_f32_16x16x32_bf16 v[114:117], v[168:171], v[176:179], 0
	v_mfma_f32_16x16x32_bf16 v[106:109], v[160:163], v[190:193], 0
	v_mfma_f32_16x16x32_bf16 v[98:101], v[168:171], v[190:193], 0
	v_mfma_f32_16x16x32_bf16 v[88:91], v[160:163], v[198:201], 0
	v_mfma_f32_16x16x32_bf16 v[80:83], v[168:171], v[198:201], 0
	v_mfma_f32_16x16x32_bf16 v[72:75], v[160:163], v[206:209], 0
	v_mfma_f32_16x16x32_bf16 v[64:67], v[168:171], v[206:209], 0
	v_mfma_f32_16x16x32_bf16 v[122:125], v[164:167], v[180:183], v[122:125]
	v_mfma_f32_16x16x32_bf16 v[114:117], v[172:175], v[180:183], v[114:117]
	v_mfma_f32_16x16x32_bf16 v[106:109], v[164:167], v[194:197], v[106:109]
	v_mfma_f32_16x16x32_bf16 v[98:101], v[172:175], v[194:197], v[98:101]
	v_mfma_f32_16x16x32_bf16 v[88:91], v[164:167], v[202:205], v[88:91]
	v_mfma_f32_16x16x32_bf16 v[80:83], v[172:175], v[202:205], v[80:83]
	v_mfma_f32_16x16x32_bf16 v[72:75], v[164:167], v[210:213], v[72:75]
	v_mfma_f32_16x16x32_bf16 v[64:67], v[172:175], v[210:213], v[64:67]
	s_setprio 0
	s_barrier
	s_add_i32 s18, s35, s47
	s_mov_b32 m0, s18
	ds_read_b128 v[176:179], v155 offset:16384
	ds_read_b128 v[180:183], v155 offset:17408
	ds_read_b128 v[190:193], v155 offset:18432
	ds_read_b128 v[194:197], v155 offset:19456
	ds_read_b128 v[198:201], v155 offset:20480
	ds_read_b128 v[202:205], v155 offset:21504
	ds_read_b128 v[206:209], v155 offset:22528
	ds_read_b128 v[210:213], v155 offset:23552
	global_load_lds_dwordx4 v134, s[44:45]
	s_add_i32 m0, s18, 0x2000
	s_add_u32 s18, s44, 0x40000
	s_addc_u32 s19, s45, 0
	s_add_i32 s35, s49, s47
	global_load_lds_dwordx4 v130, s[44:45]
	s_mov_b32 m0, s35
	s_nop 0
	global_load_lds_dwordx4 v134, s[18:19]
	s_add_i32 m0, s35, 0x2000
	s_nop 0
	global_load_lds_dwordx4 v130, s[18:19]
	s_waitcnt vmcnt(6)
	s_waitcnt lgkmcnt(0)
	s_barrier
	s_setprio 1
	s_waitcnt lgkmcnt(0)
	v_mfma_f32_16x16x32_bf16 v[60:63], v[138:141], v[176:179], 0
	v_mfma_f32_16x16x32_bf16 v[52:55], v[146:149], v[176:179], 0
	v_mfma_f32_16x16x32_bf16 v[44:47], v[138:141], v[190:193], 0
	v_mfma_f32_16x16x32_bf16 v[36:39], v[146:149], v[190:193], 0
	v_mfma_f32_16x16x32_bf16 v[28:31], v[138:141], v[198:201], 0
	v_mfma_f32_16x16x32_bf16 v[20:23], v[146:149], v[198:201], 0
	v_mfma_f32_16x16x32_bf16 v[12:15], v[138:141], v[206:209], 0
	v_mfma_f32_16x16x32_bf16 v[4:7], v[146:149], v[206:209], 0
	v_mfma_f32_16x16x32_bf16 v[60:63], v[142:145], v[180:183], v[60:63]
	v_mfma_f32_16x16x32_bf16 v[52:55], v[156:159], v[180:183], v[52:55]
	v_mfma_f32_16x16x32_bf16 v[44:47], v[142:145], v[194:197], v[44:47]
	v_mfma_f32_16x16x32_bf16 v[36:39], v[156:159], v[194:197], v[36:39]
	v_mfma_f32_16x16x32_bf16 v[28:31], v[142:145], v[202:205], v[28:31]
	v_mfma_f32_16x16x32_bf16 v[20:23], v[156:159], v[202:205], v[20:23]
	v_mfma_f32_16x16x32_bf16 v[12:15], v[142:145], v[210:213], v[12:15]
	v_mfma_f32_16x16x32_bf16 v[4:7], v[156:159], v[210:213], v[4:7]
	v_mfma_f32_16x16x32_bf16 v[56:59], v[160:163], v[176:179], 0
	v_mfma_f32_16x16x32_bf16 v[48:51], v[168:171], v[176:179], 0
	v_mfma_f32_16x16x32_bf16 v[40:43], v[160:163], v[190:193], 0
	v_mfma_f32_16x16x32_bf16 v[32:35], v[168:171], v[190:193], 0
	v_mfma_f32_16x16x32_bf16 v[24:27], v[160:163], v[198:201], 0
	v_mfma_f32_16x16x32_bf16 v[16:19], v[168:171], v[198:201], 0
	v_mfma_f32_16x16x32_bf16 v[8:11], v[160:163], v[206:209], 0
	v_mfma_f32_16x16x32_bf16 v[0:3], v[168:171], v[206:209], 0
	v_mfma_f32_16x16x32_bf16 v[56:59], v[164:167], v[180:183], v[56:59]
	v_mfma_f32_16x16x32_bf16 v[48:51], v[172:175], v[180:183], v[48:51]
	v_mfma_f32_16x16x32_bf16 v[40:43], v[164:167], v[194:197], v[40:43]
	v_mfma_f32_16x16x32_bf16 v[32:35], v[172:175], v[194:197], v[32:35]
	v_mfma_f32_16x16x32_bf16 v[24:27], v[164:167], v[202:205], v[24:27]
	v_mfma_f32_16x16x32_bf16 v[16:19], v[172:175], v[202:205], v[16:19]
	v_mfma_f32_16x16x32_bf16 v[8:11], v[164:167], v[210:213], v[8:11]
	v_mfma_f32_16x16x32_bf16 v[0:3], v[172:175], v[210:213], v[0:3]
	s_setprio 0
	s_barrier
	s_add_i32 s35, 0, 0x18000
	v_add_u32_e32 v96, s35, v151
	s_add_i32 s44, 0, 0x1c000
	ds_read_b128 v[138:141], v96
	ds_read_b128 v[142:145], v96 offset:1024
	ds_read_b128 v[146:149], v96 offset:2048
	ds_read_b128 v[156:159], v96 offset:3072
	v_add_u32_e32 v96, s44, v151
	ds_read_b128 v[160:163], v96
	ds_read_b128 v[164:167], v96 offset:1024
	ds_read_b128 v[168:171], v96 offset:2048
	ds_read_b128 v[172:175], v96 offset:3072
	s_mov_b32 m0, s65
	s_nop 0
	global_load_lds_dwordx4 v136, s[42:43]
	s_mov_b32 m0, s72
	s_nop 0
	global_load_lds_dwordx4 v132, s[42:43]
	s_add_u32 s18, s42, 0x40000
	s_addc_u32 s19, s43, 0
	s_mov_b32 m0, s73
	ds_read_b128 v[176:179], v155 offset:32768
	ds_read_b128 v[180:183], v155 offset:33792
	ds_read_b128 v[190:193], v155 offset:34816
	ds_read_b128 v[194:197], v155 offset:35840
	ds_read_b128 v[198:201], v155 offset:36864
	ds_read_b128 v[202:205], v155 offset:37888
	ds_read_b128 v[206:209], v155 offset:38912
	ds_read_b128 v[210:213], v155 offset:39936
	global_load_lds_dwordx4 v136, s[18:19]
	s_mov_b32 m0, s74
	s_nop 0
	global_load_lds_dwordx4 v132, s[18:19]
	s_waitcnt vmcnt(8)
	s_waitcnt lgkmcnt(0)
	s_barrier
	s_setprio 1
	s_waitcnt lgkmcnt(0)
	v_mfma_f32_16x16x32_bf16 v[126:129], v[138:141], v[176:179], v[126:129]
	v_mfma_f32_16x16x32_bf16 v[118:121], v[146:149], v[176:179], v[118:121]
	v_mfma_f32_16x16x32_bf16 v[110:113], v[138:141], v[190:193], v[110:113]
	v_mfma_f32_16x16x32_bf16 v[102:105], v[146:149], v[190:193], v[102:105]
	v_mfma_f32_16x16x32_bf16 v[92:95], v[138:141], v[198:201], v[92:95]
	v_mfma_f32_16x16x32_bf16 v[84:87], v[146:149], v[198:201], v[84:87]
	v_mfma_f32_16x16x32_bf16 v[76:79], v[138:141], v[206:209], v[76:79]
	v_mfma_f32_16x16x32_bf16 v[68:71], v[146:149], v[206:209], v[68:71]
	v_mfma_f32_16x16x32_bf16 v[126:129], v[142:145], v[180:183], v[126:129]
	v_mfma_f32_16x16x32_bf16 v[118:121], v[156:159], v[180:183], v[118:121]
	v_mfma_f32_16x16x32_bf16 v[110:113], v[142:145], v[194:197], v[110:113]
	v_mfma_f32_16x16x32_bf16 v[102:105], v[156:159], v[194:197], v[102:105]
	v_mfma_f32_16x16x32_bf16 v[92:95], v[142:145], v[202:205], v[92:95]
	v_mfma_f32_16x16x32_bf16 v[84:87], v[156:159], v[202:205], v[84:87]
	v_mfma_f32_16x16x32_bf16 v[76:79], v[142:145], v[210:213], v[76:79]
	v_mfma_f32_16x16x32_bf16 v[68:71], v[156:159], v[210:213], v[68:71]
	v_mfma_f32_16x16x32_bf16 v[122:125], v[160:163], v[176:179], v[122:125]
	v_mfma_f32_16x16x32_bf16 v[114:117], v[168:171], v[176:179], v[114:117]
	v_mfma_f32_16x16x32_bf16 v[106:109], v[160:163], v[190:193], v[106:109]
	v_mfma_f32_16x16x32_bf16 v[98:101], v[168:171], v[190:193], v[98:101]
	v_mfma_f32_16x16x32_bf16 v[88:91], v[160:163], v[198:201], v[88:91]
	v_mfma_f32_16x16x32_bf16 v[80:83], v[168:171], v[198:201], v[80:83]
	v_mfma_f32_16x16x32_bf16 v[72:75], v[160:163], v[206:209], v[72:75]
	v_mfma_f32_16x16x32_bf16 v[64:67], v[168:171], v[206:209], v[64:67]
	v_mfma_f32_16x16x32_bf16 v[122:125], v[164:167], v[180:183], v[122:125]
	v_mfma_f32_16x16x32_bf16 v[114:117], v[172:175], v[180:183], v[114:117]
	v_mfma_f32_16x16x32_bf16 v[106:109], v[164:167], v[194:197], v[106:109]
	v_mfma_f32_16x16x32_bf16 v[98:101], v[172:175], v[194:197], v[98:101]
	v_mfma_f32_16x16x32_bf16 v[88:91], v[164:167], v[202:205], v[88:91]
	v_mfma_f32_16x16x32_bf16 v[80:83], v[172:175], v[202:205], v[80:83]
	v_mfma_f32_16x16x32_bf16 v[72:75], v[164:167], v[210:213], v[72:75]
	v_mfma_f32_16x16x32_bf16 v[64:67], v[172:175], v[210:213], v[64:67]
	s_setprio 0
	s_barrier
	s_add_i32 s18, s35, s47
	s_mov_b32 m0, s18
	ds_read_b128 v[176:179], v155 offset:49152
	ds_read_b128 v[180:183], v155 offset:50176
	ds_read_b128 v[190:193], v155 offset:51200
	ds_read_b128 v[194:197], v155 offset:52224
	ds_read_b128 v[198:201], v155 offset:53248
	ds_read_b128 v[202:205], v155 offset:54272
	ds_read_b128 v[206:209], v155 offset:55296
	ds_read_b128 v[210:213], v155 offset:56320
	global_load_lds_dwordx4 v134, s[68:69]
	s_add_i32 m0, s18, 0x2000
	s_add_u32 s18, s68, 0x40000
	s_addc_u32 s19, s69, 0
	s_add_i32 s35, s44, s47
	global_load_lds_dwordx4 v130, s[68:69]
	s_mov_b32 m0, s35
	s_nop 0
	global_load_lds_dwordx4 v134, s[18:19]
	s_add_i32 m0, s35, 0x2000
	s_nop 0
	global_load_lds_dwordx4 v130, s[18:19]
	s_waitcnt vmcnt(6)
	s_waitcnt lgkmcnt(0)
	s_barrier
	s_setprio 1
	s_waitcnt lgkmcnt(0)
	v_mfma_f32_16x16x32_bf16 v[60:63], v[138:141], v[176:179], v[60:63]
	v_mfma_f32_16x16x32_bf16 v[52:55], v[146:149], v[176:179], v[52:55]
	v_mfma_f32_16x16x32_bf16 v[44:47], v[138:141], v[190:193], v[44:47]
	v_mfma_f32_16x16x32_bf16 v[36:39], v[146:149], v[190:193], v[36:39]
	v_mfma_f32_16x16x32_bf16 v[28:31], v[138:141], v[198:201], v[28:31]
	v_mfma_f32_16x16x32_bf16 v[20:23], v[146:149], v[198:201], v[20:23]
	v_mfma_f32_16x16x32_bf16 v[12:15], v[138:141], v[206:209], v[12:15]
	v_mfma_f32_16x16x32_bf16 v[4:7], v[146:149], v[206:209], v[4:7]
	v_mfma_f32_16x16x32_bf16 v[60:63], v[142:145], v[180:183], v[60:63]
	v_mfma_f32_16x16x32_bf16 v[52:55], v[156:159], v[180:183], v[52:55]
	v_mfma_f32_16x16x32_bf16 v[44:47], v[142:145], v[194:197], v[44:47]
	v_mfma_f32_16x16x32_bf16 v[36:39], v[156:159], v[194:197], v[36:39]
	v_mfma_f32_16x16x32_bf16 v[28:31], v[142:145], v[202:205], v[28:31]
	v_mfma_f32_16x16x32_bf16 v[20:23], v[156:159], v[202:205], v[20:23]
	v_mfma_f32_16x16x32_bf16 v[12:15], v[142:145], v[210:213], v[12:15]
	v_mfma_f32_16x16x32_bf16 v[4:7], v[156:159], v[210:213], v[4:7]
	v_mfma_f32_16x16x32_bf16 v[56:59], v[160:163], v[176:179], v[56:59]
	v_mfma_f32_16x16x32_bf16 v[48:51], v[168:171], v[176:179], v[48:51]
	v_mfma_f32_16x16x32_bf16 v[40:43], v[160:163], v[190:193], v[40:43]
	v_mfma_f32_16x16x32_bf16 v[32:35], v[168:171], v[190:193], v[32:35]
	v_mfma_f32_16x16x32_bf16 v[24:27], v[160:163], v[198:201], v[24:27]
	v_mfma_f32_16x16x32_bf16 v[16:19], v[168:171], v[198:201], v[16:19]
	v_mfma_f32_16x16x32_bf16 v[8:11], v[160:163], v[206:209], v[8:11]
	v_mfma_f32_16x16x32_bf16 v[0:3], v[168:171], v[206:209], v[0:3]
	v_mfma_f32_16x16x32_bf16 v[56:59], v[164:167], v[180:183], v[56:59]
	v_mfma_f32_16x16x32_bf16 v[48:51], v[172:175], v[180:183], v[48:51]
	v_mfma_f32_16x16x32_bf16 v[40:43], v[164:167], v[194:197], v[40:43]
	v_mfma_f32_16x16x32_bf16 v[32:35], v[172:175], v[194:197], v[32:35]
	v_mfma_f32_16x16x32_bf16 v[24:27], v[164:167], v[202:205], v[24:27]
	v_mfma_f32_16x16x32_bf16 v[16:19], v[172:175], v[202:205], v[16:19]
	v_mfma_f32_16x16x32_bf16 v[8:11], v[164:167], v[210:213], v[8:11]
	v_mfma_f32_16x16x32_bf16 v[0:3], v[172:175], v[210:213], v[0:3]
	s_setprio 0
	s_barrier
	s_add_i32 s85, s85, 2
	s_add_u32 s83, s83, 0x100
	s_addc_u32 s84, s84, 0
	s_cmp_gt_u32 s85, 13
	s_cbranch_scc0 .LBB0_740
